# GU K-loops: early wave group's vmcnt(8) moved from the end of its load cluster to the end of its MFMA cluster
# speedup vs baseline: 1.0156x; 1.0046x over previous
.LBB0_1680:
	ds_read_b128 v[142:145], v138
	ds_read_b128 v[146:149], v138 offset:1024
	ds_read_b128 v[150:153], v138 offset:2048
	ds_read_b128 v[154:157], v138 offset:3072
	ds_read_b128 v[158:161], v139
	ds_read_b128 v[162:165], v139 offset:1024
	ds_read_b128 v[166:169], v139 offset:2048
	ds_read_b128 v[170:173], v139 offset:3072
	s_add_u32 s34, s30, 0xfffc0080
	s_addc_u32 s35, s31, -1
	s_cmp_eq_u32 s49, 12
	s_cselect_b32 s35, s23, s35
	s_cselect_b32 s34, s22, s34
	s_cselect_b32 s37, s25, s48
	s_cselect_b32 s36, s24, s21
	v_mov_b32_e32 v128, v133
	v_mov_b32_e32 v130, v134
	s_add_i32 m0, s41, 0xc000
	ds_read_b128 v[174:177], v140
	ds_read_b128 v[178:181], v140 offset:1024
	ds_read_b128 v[182:185], v140 offset:2048
	ds_read_b128 v[186:189], v140 offset:3072
	ds_read_b128 v[190:193], v140 offset:4096
	ds_read_b128 v[194:197], v140 offset:5120
	ds_read_b128 v[198:201], v140 offset:6144
	ds_read_b128 v[202:205], v140 offset:7168
	s_nop 0
	global_load_lds_dwordx4 v128, s[30:31]
	s_add_i32 m0, s41, 0xe000
	s_nop 0
	global_load_lds_dwordx4 v130, s[30:31]
	s_and_b64 vcc, exec, s[14:15]
	s_cbranch_vccnz .Lmy_lw_1
	s_waitcnt vmcnt(8)
.Lmy_lw_1:
	s_waitcnt lgkmcnt(0)
	s_barrier
	s_setprio 1
	s_waitcnt lgkmcnt(0)
	v_mfma_scale_f32_16x16x128_f8f6f4 v[124:127], v[142:149], v[174:181], v[124:127], v141, v141 op_sel_hi:[0,0,0]
	v_mfma_scale_f32_16x16x128_f8f6f4 v[116:119], v[150:157], v[174:181], v[116:119], v141, v141 op_sel_hi:[0,0,0]
	v_mfma_scale_f32_16x16x128_f8f6f4 v[108:111], v[142:149], v[182:189], v[108:111], v141, v141 op_sel_hi:[0,0,0]
	v_mfma_scale_f32_16x16x128_f8f6f4 v[100:103], v[150:157], v[182:189], v[100:103], v141, v141 op_sel_hi:[0,0,0]
	v_mfma_scale_f32_16x16x128_f8f6f4 v[206:209], v[142:149], v[190:197], v[92:95], v141, v141 op_sel_hi:[0,0,0]
	v_mfma_scale_f32_16x16x128_f8f6f4 v[210:213], v[150:157], v[190:197], v[84:87], v141, v141 op_sel_hi:[0,0,0]
	v_mfma_scale_f32_16x16x128_f8f6f4 v[214:217], v[142:149], v[198:205], v[76:79], v141, v141 op_sel_hi:[0,0,0]
	v_mfma_scale_f32_16x16x128_f8f6f4 v[218:221], v[150:157], v[198:205], v[68:71], v141, v141 op_sel_hi:[0,0,0]
	s_setprio 0
	s_setprio 1
	v_mfma_scale_f32_16x16x128_f8f6f4 v[120:123], v[158:165], v[174:181], v[120:123], v141, v141 op_sel_hi:[0,0,0]
	v_mfma_scale_f32_16x16x128_f8f6f4 v[112:115], v[166:173], v[174:181], v[112:115], v141, v141 op_sel_hi:[0,0,0]
	v_mfma_scale_f32_16x16x128_f8f6f4 v[104:107], v[158:165], v[182:189], v[104:107], v141, v141 op_sel_hi:[0,0,0]
	v_mfma_scale_f32_16x16x128_f8f6f4 v[96:99], v[166:173], v[182:189], v[96:99], v141, v141 op_sel_hi:[0,0,0]
	v_mfma_scale_f32_16x16x128_f8f6f4 v[174:177], v[158:165], v[190:197], v[88:91], v141, v141 op_sel_hi:[0,0,0]
	v_mfma_scale_f32_16x16x128_f8f6f4 v[178:181], v[166:173], v[190:197], v[80:83], v141, v141 op_sel_hi:[0,0,0]
	v_mfma_scale_f32_16x16x128_f8f6f4 v[182:185], v[158:165], v[198:205], v[72:75], v141, v141 op_sel_hi:[0,0,0]
	v_mfma_scale_f32_16x16x128_f8f6f4 v[186:189], v[166:173], v[198:205], v[64:67], v141, v141 op_sel_hi:[0,0,0]
	s_setprio 0
	s_waitcnt vmcnt(8)
	s_barrier
	s_add_i32 s64, s54, s3
	v_mov_b32_e32 v128, v135
	v_mov_b32_e32 v130, v136
	s_mov_b32 m0, s64
	s_nop 0
	ds_read_b128 v[64:67], v140 offset:16384
	ds_read_b128 v[68:71], v140 offset:17408
	ds_read_b128 v[72:75], v140 offset:18432
	ds_read_b128 v[76:79], v140 offset:19456
	ds_read_b128 v[80:83], v140 offset:20480
	ds_read_b128 v[84:87], v140 offset:21504
	ds_read_b128 v[88:91], v140 offset:22528
	ds_read_b128 v[92:95], v140 offset:23552
	v_mov_b32_e32 v131, v129
	global_load_lds_dwordx4 v128, s[36:37]
	s_add_i32 m0, s64, 0x2000
	v_mov_b32_e32 v128, v135
	global_load_lds_dwordx4 v130, s[36:37]
	v_mov_b32_e32 v130, v136
	s_add_i32 s64, s55, s3
	v_lshl_add_u64 v[190:191], s[36:37], 0, v[128:129]
	v_lshl_add_u64 v[190:191], v[190:191], 0, s[8:9]
	s_mov_b32 m0, s64
	v_lshl_add_u64 v[130:131], s[36:37], 0, v[130:131]
	global_load_lds_dwordx4 v[190:191], off
	v_lshl_add_u64 v[130:131], v[130:131], 0, s[8:9]
	s_add_i32 m0, s64, 0x2000
	v_mov_b32_e32 v128, v133
	global_load_lds_dwordx4 v[130:131], off
	v_mov_b32_e32 v130, v134
	s_mov_b32 m0, s41
	s_nop 0
	global_load_lds_dwordx4 v128, s[34:35]
	s_mov_b32 m0, s42
	s_nop 0
	global_load_lds_dwordx4 v130, s[34:35]
	s_and_b64 vcc, exec, s[14:15]
	s_cbranch_vccnz .Lmy_lw_2
	s_waitcnt vmcnt(8)
.Lmy_lw_2:
	s_waitcnt lgkmcnt(0)
	s_barrier
	s_setprio 1
	s_waitcnt lgkmcnt(0)
	v_mfma_scale_f32_16x16x128_f8f6f4 v[60:63], v[142:149], v[64:71], v[60:63], v141, v141 op_sel_hi:[0,0,0]
	v_mfma_scale_f32_16x16x128_f8f6f4 v[52:55], v[150:157], v[64:71], v[52:55], v141, v141 op_sel_hi:[0,0,0]
	v_mfma_scale_f32_16x16x128_f8f6f4 v[44:47], v[142:149], v[72:79], v[44:47], v141, v141 op_sel_hi:[0,0,0]
	v_mfma_scale_f32_16x16x128_f8f6f4 v[198:201], v[150:157], v[72:79], v[36:39], v141, v141 op_sel_hi:[0,0,0]
	v_mfma_scale_f32_16x16x128_f8f6f4 v[202:205], v[142:149], v[80:87], v[28:31], v141, v141 op_sel_hi:[0,0,0]
	v_mfma_scale_f32_16x16x128_f8f6f4 v[222:225], v[150:157], v[80:87], v[20:23], v141, v141 op_sel_hi:[0,0,0]
	v_mfma_scale_f32_16x16x128_f8f6f4 v[226:229], v[142:149], v[88:95], v[12:15], v141, v141 op_sel_hi:[0,0,0]
	v_mfma_scale_f32_16x16x128_f8f6f4 v[230:233], v[150:157], v[88:95], v[4:7], v141, v141 op_sel_hi:[0,0,0]
	s_setprio 0
	s_setprio 1
	v_mfma_scale_f32_16x16x128_f8f6f4 v[56:59], v[158:165], v[64:71], v[56:59], v141, v141 op_sel_hi:[0,0,0]
	v_mfma_scale_f32_16x16x128_f8f6f4 v[48:51], v[166:173], v[64:71], v[48:51], v141, v141 op_sel_hi:[0,0,0]
	v_mfma_scale_f32_16x16x128_f8f6f4 v[40:43], v[158:165], v[72:79], v[40:43], v141, v141 op_sel_hi:[0,0,0]
	v_mfma_scale_f32_16x16x128_f8f6f4 v[234:237], v[166:173], v[72:79], v[32:35], v141, v141 op_sel_hi:[0,0,0]
	v_mfma_scale_f32_16x16x128_f8f6f4 v[238:241], v[158:165], v[80:87], v[24:27], v141, v141 op_sel_hi:[0,0,0]
	v_mfma_scale_f32_16x16x128_f8f6f4 v[242:245], v[166:173], v[80:87], v[16:19], v141, v141 op_sel_hi:[0,0,0]
	v_mfma_scale_f32_16x16x128_f8f6f4 v[246:249], v[158:165], v[88:95], v[8:11], v141, v141 op_sel_hi:[0,0,0]
	v_mfma_scale_f32_16x16x128_f8f6f4 v[250:253], v[166:173], v[88:95], v[0:3], v141, v141 op_sel_hi:[0,0,0]
	s_setprio 0
	s_waitcnt vmcnt(8)
	s_barrier
	s_add_i32 s66, 0, 0x18000
	s_nop 2
	v_add_u32_e32 v8, s66, v137
	s_add_i32 s67, 0, 0x1c000
	ds_read_b128 v[0:3], v8
	ds_read_b128 v[4:7], v8 offset:1024
	ds_read_b128 v[142:145], v8 offset:2048
	ds_read_b128 v[146:149], v8 offset:3072
	v_add_u32_e32 v8, s67, v137
	ds_read_b128 v[150:153], v8
	ds_read_b128 v[154:157], v8 offset:1024
	ds_read_b128 v[158:161], v8 offset:2048
	ds_read_b128 v[162:165], v8 offset:3072
	s_add_u32 s64, s34, 0x40000
	v_mov_b32_e32 v64, v133
	v_mov_b32_e32 v65, v134
	s_addc_u32 s65, s35, 0
	s_mov_b32 m0, s43
	ds_read_b128 v[8:11], v140 offset:32768
	ds_read_b128 v[12:15], v140 offset:33792
	ds_read_b128 v[16:19], v140 offset:34816
	ds_read_b128 v[20:23], v140 offset:35840
	ds_read_b128 v[24:27], v140 offset:36864
	ds_read_b128 v[28:31], v140 offset:37888
	ds_read_b128 v[32:35], v140 offset:38912
	ds_read_b128 v[36:39], v140 offset:39936
	s_nop 0
	global_load_lds_dwordx4 v64, s[64:65]
	s_mov_b32 m0, s44
	s_nop 0
	global_load_lds_dwordx4 v65, s[64:65]
	s_and_b64 vcc, exec, s[14:15]
	s_cbranch_vccnz .Lmy_lw_3
	s_waitcnt vmcnt(8)
.Lmy_lw_3:
	s_waitcnt lgkmcnt(0)
	s_barrier
	s_setprio 1
	s_waitcnt lgkmcnt(0)
	v_mfma_scale_f32_16x16x128_f8f6f4 v[124:127], v[0:7], v[8:15], v[124:127], v141, v141 op_sel_hi:[0,0,0]
	v_mfma_scale_f32_16x16x128_f8f6f4 v[116:119], v[142:149], v[8:15], v[116:119], v141, v141 op_sel_hi:[0,0,0]
	v_mfma_scale_f32_16x16x128_f8f6f4 v[108:111], v[0:7], v[16:23], v[108:111], v141, v141 op_sel_hi:[0,0,0]
	v_mfma_scale_f32_16x16x128_f8f6f4 v[100:103], v[142:149], v[16:23], v[100:103], v141, v141 op_sel_hi:[0,0,0]
	v_mfma_scale_f32_16x16x128_f8f6f4 v[92:95], v[0:7], v[24:31], v[206:209], v141, v141 op_sel_hi:[0,0,0]
	v_mfma_scale_f32_16x16x128_f8f6f4 v[84:87], v[142:149], v[24:31], v[210:213], v141, v141 op_sel_hi:[0,0,0]
	v_mfma_scale_f32_16x16x128_f8f6f4 v[76:79], v[0:7], v[32:39], v[214:217], v141, v141 op_sel_hi:[0,0,0]
	v_mfma_scale_f32_16x16x128_f8f6f4 v[68:71], v[142:149], v[32:39], v[218:221], v141, v141 op_sel_hi:[0,0,0]
	s_setprio 0
	s_setprio 1
	v_mfma_scale_f32_16x16x128_f8f6f4 v[120:123], v[150:157], v[8:15], v[120:123], v141, v141 op_sel_hi:[0,0,0]
	v_mfma_scale_f32_16x16x128_f8f6f4 v[112:115], v[158:165], v[8:15], v[112:115], v141, v141 op_sel_hi:[0,0,0]
	v_mfma_scale_f32_16x16x128_f8f6f4 v[104:107], v[150:157], v[16:23], v[104:107], v141, v141 op_sel_hi:[0,0,0]
	v_mfma_scale_f32_16x16x128_f8f6f4 v[96:99], v[158:165], v[16:23], v[96:99], v141, v141 op_sel_hi:[0,0,0]
	v_mfma_scale_f32_16x16x128_f8f6f4 v[88:91], v[150:157], v[24:31], v[174:177], v141, v141 op_sel_hi:[0,0,0]
	v_mfma_scale_f32_16x16x128_f8f6f4 v[80:83], v[158:165], v[24:31], v[178:181], v141, v141 op_sel_hi:[0,0,0]
	v_mfma_scale_f32_16x16x128_f8f6f4 v[72:75], v[150:157], v[32:39], v[182:185], v141, v141 op_sel_hi:[0,0,0]
	v_mfma_scale_f32_16x16x128_f8f6f4 v[64:67], v[158:165], v[32:39], v[186:189], v141, v141 op_sel_hi:[0,0,0]
	s_setprio 0
	s_waitcnt vmcnt(8)
	s_barrier
	s_add_u32 s64, s36, 0x80000
	s_addc_u32 s65, s37, 0
	s_add_i32 s66, s66, s3
	v_mov_b32_e32 v8, v135
	v_mov_b32_e32 v9, v136
	s_mov_b32 m0, s66
	ds_read_b128 v[166:169], v140 offset:49152
	ds_read_b128 v[170:173], v140 offset:50176
	ds_read_b128 v[174:177], v140 offset:51200
	ds_read_b128 v[178:181], v140 offset:52224
	ds_read_b128 v[182:185], v140 offset:53248
	ds_read_b128 v[186:189], v140 offset:54272
	ds_read_b128 v[190:193], v140 offset:55296
	ds_read_b128 v[194:197], v140 offset:56320
	v_mov_b32_e32 v128, v133
	global_load_lds_dwordx4 v8, s[64:65]
	s_add_i32 m0, s66, 0x2000
	s_add_u32 s36, s36, 0x80800
	global_load_lds_dwordx4 v9, s[64:65]
	v_mov_b32_e32 v8, v135
	v_mov_b32_e32 v9, v136
	s_addc_u32 s37, s37, 0
	s_add_i32 s64, s67, s3
	s_mov_b32 m0, s64
	s_nop 0
	global_load_lds_dwordx4 v8, s[36:37]
	s_add_i32 m0, s64, 0x2000
	v_mov_b32_e32 v8, v134
	global_load_lds_dwordx4 v9, s[36:37]
	v_mov_b32_e32 v9, v129
	v_lshl_add_u64 v[10:11], s[34:35], 0, v[128:129]
	v_lshl_add_u64 v[10:11], v[10:11], 0, s[12:13]
	s_mov_b32 m0, s47
	v_lshl_add_u64 v[8:9], s[34:35], 0, v[8:9]
	global_load_lds_dwordx4 v[10:11], off
	v_lshl_add_u64 v[8:9], v[8:9], 0, s[12:13]
	s_mov_b32 m0, s52
	s_nop 0
	global_load_lds_dwordx4 v[8:9], off
	s_and_b64 vcc, exec, s[14:15]
	s_cbranch_vccnz .Lmy_lw_4
	s_waitcnt vmcnt(8)
.Lmy_lw_4:
	s_waitcnt lgkmcnt(0)
	s_barrier
	s_setprio 1
	s_waitcnt lgkmcnt(0)
	v_mfma_scale_f32_16x16x128_f8f6f4 v[60:63], v[0:7], v[166:173], v[60:63], v141, v141 op_sel_hi:[0,0,0]
	v_mfma_scale_f32_16x16x128_f8f6f4 v[52:55], v[142:149], v[166:173], v[52:55], v141, v141 op_sel_hi:[0,0,0]
	v_mfma_scale_f32_16x16x128_f8f6f4 v[44:47], v[0:7], v[174:181], v[44:47], v141, v141 op_sel_hi:[0,0,0]
	v_mfma_scale_f32_16x16x128_f8f6f4 v[36:39], v[142:149], v[174:181], v[198:201], v141, v141 op_sel_hi:[0,0,0]
	v_mfma_scale_f32_16x16x128_f8f6f4 v[28:31], v[0:7], v[182:189], v[202:205], v141, v141 op_sel_hi:[0,0,0]
	v_mfma_scale_f32_16x16x128_f8f6f4 v[20:23], v[142:149], v[182:189], v[222:225], v141, v141 op_sel_hi:[0,0,0]
	v_mfma_scale_f32_16x16x128_f8f6f4 v[12:15], v[0:7], v[190:197], v[226:229], v141, v141 op_sel_hi:[0,0,0]
	v_mfma_scale_f32_16x16x128_f8f6f4 v[4:7], v[142:149], v[190:197], v[230:233], v141, v141 op_sel_hi:[0,0,0]
	s_setprio 0
	s_setprio 1
	v_mfma_scale_f32_16x16x128_f8f6f4 v[56:59], v[150:157], v[166:173], v[56:59], v141, v141 op_sel_hi:[0,0,0]
	v_mfma_scale_f32_16x16x128_f8f6f4 v[48:51], v[158:165], v[166:173], v[48:51], v141, v141 op_sel_hi:[0,0,0]
	v_mfma_scale_f32_16x16x128_f8f6f4 v[40:43], v[150:157], v[174:181], v[40:43], v141, v141 op_sel_hi:[0,0,0]
	v_mfma_scale_f32_16x16x128_f8f6f4 v[32:35], v[158:165], v[174:181], v[234:237], v141, v141 op_sel_hi:[0,0,0]
	v_mfma_scale_f32_16x16x128_f8f6f4 v[24:27], v[150:157], v[182:189], v[238:241], v141, v141 op_sel_hi:[0,0,0]
	v_mfma_scale_f32_16x16x128_f8f6f4 v[16:19], v[158:165], v[182:189], v[242:245], v141, v141 op_sel_hi:[0,0,0]
	v_mfma_scale_f32_16x16x128_f8f6f4 v[8:11], v[150:157], v[190:197], v[246:249], v141, v141 op_sel_hi:[0,0,0]
	v_mfma_scale_f32_16x16x128_f8f6f4 v[0:3], v[158:165], v[190:197], v[250:253], v141, v141 op_sel_hi:[0,0,0]
	s_setprio 0
	s_waitcnt vmcnt(8)
	s_barrier
	s_add_i32 s49, s49, 2
	s_add_u32 s21, s21, 0x100000
	s_addc_u32 s48, s48, 0
	s_add_u32 s30, s30, 0x100
	s_addc_u32 s31, s31, 0
	s_cmp_gt_u32 s49, 13
	s_cbranch_scc0 .LBB0_1680
	s_and_b64 vcc, exec, s[14:15]
	s_cbranch_vccz .LBB0_1683
	s_barrier

.LBB0_2893:
	ds_read_b128 v[142:145], v138
	ds_read_b128 v[146:149], v138 offset:1024
	ds_read_b128 v[150:153], v138 offset:2048
	ds_read_b128 v[154:157], v138 offset:3072
	ds_read_b128 v[158:161], v139
	ds_read_b128 v[162:165], v139 offset:1024
	ds_read_b128 v[166:169], v139 offset:2048
	ds_read_b128 v[170:173], v139 offset:3072
	s_add_u32 s34, s30, 0xfffc0080
	s_addc_u32 s35, s31, -1
	s_cmp_eq_u32 s54, 12
	s_cselect_b32 s35, s23, s35
	s_cselect_b32 s34, s22, s34
	s_cselect_b32 s37, s25, s53
	s_cselect_b32 s36, s24, s21
	v_mov_b32_e32 v128, v133
	v_mov_b32_e32 v130, v134
	s_add_i32 m0, s41, 0xc000
	ds_read_b128 v[174:177], v140
	ds_read_b128 v[178:181], v140 offset:1024
	ds_read_b128 v[182:185], v140 offset:2048
	ds_read_b128 v[186:189], v140 offset:3072
	ds_read_b128 v[190:193], v140 offset:4096
	ds_read_b128 v[194:197], v140 offset:5120
	ds_read_b128 v[198:201], v140 offset:6144
	ds_read_b128 v[202:205], v140 offset:7168
	s_nop 0
	global_load_lds_dwordx4 v128, s[30:31]
	s_add_i32 m0, s41, 0xe000
	s_nop 0
	global_load_lds_dwordx4 v130, s[30:31]
	s_and_b64 vcc, exec, s[14:15]
	s_cbranch_vccnz .Lmy_lw_5
	s_waitcnt vmcnt(8)
.Lmy_lw_5:
	s_waitcnt lgkmcnt(0)
	s_barrier
	s_setprio 1
	s_waitcnt lgkmcnt(0)
	v_mfma_scale_f32_16x16x128_f8f6f4 v[124:127], v[142:149], v[174:181], v[124:127], v141, v141 op_sel_hi:[0,0,0]
	v_mfma_scale_f32_16x16x128_f8f6f4 v[116:119], v[150:157], v[174:181], v[116:119], v141, v141 op_sel_hi:[0,0,0]
	v_mfma_scale_f32_16x16x128_f8f6f4 v[108:111], v[142:149], v[182:189], v[108:111], v141, v141 op_sel_hi:[0,0,0]
	v_mfma_scale_f32_16x16x128_f8f6f4 v[100:103], v[150:157], v[182:189], v[100:103], v141, v141 op_sel_hi:[0,0,0]
	v_mfma_scale_f32_16x16x128_f8f6f4 v[206:209], v[142:149], v[190:197], v[92:95], v141, v141 op_sel_hi:[0,0,0]
	v_mfma_scale_f32_16x16x128_f8f6f4 v[210:213], v[150:157], v[190:197], v[84:87], v141, v141 op_sel_hi:[0,0,0]
	v_mfma_scale_f32_16x16x128_f8f6f4 v[214:217], v[142:149], v[198:205], v[76:79], v141, v141 op_sel_hi:[0,0,0]
	v_mfma_scale_f32_16x16x128_f8f6f4 v[218:221], v[150:157], v[198:205], v[68:71], v141, v141 op_sel_hi:[0,0,0]
	s_setprio 0
	s_setprio 1
	v_mfma_scale_f32_16x16x128_f8f6f4 v[120:123], v[158:165], v[174:181], v[120:123], v141, v141 op_sel_hi:[0,0,0]
	v_mfma_scale_f32_16x16x128_f8f6f4 v[112:115], v[166:173], v[174:181], v[112:115], v141, v141 op_sel_hi:[0,0,0]
	v_mfma_scale_f32_16x16x128_f8f6f4 v[104:107], v[158:165], v[182:189], v[104:107], v141, v141 op_sel_hi:[0,0,0]
	v_mfma_scale_f32_16x16x128_f8f6f4 v[96:99], v[166:173], v[182:189], v[96:99], v141, v141 op_sel_hi:[0,0,0]
	v_mfma_scale_f32_16x16x128_f8f6f4 v[174:177], v[158:165], v[190:197], v[88:91], v141, v141 op_sel_hi:[0,0,0]
	v_mfma_scale_f32_16x16x128_f8f6f4 v[178:181], v[166:173], v[190:197], v[80:83], v141, v141 op_sel_hi:[0,0,0]
	v_mfma_scale_f32_16x16x128_f8f6f4 v[182:185], v[158:165], v[198:205], v[72:75], v141, v141 op_sel_hi:[0,0,0]
	v_mfma_scale_f32_16x16x128_f8f6f4 v[186:189], v[166:173], v[198:205], v[64:67], v141, v141 op_sel_hi:[0,0,0]
	s_setprio 0
	s_waitcnt vmcnt(8)
	s_barrier
	s_add_i32 s55, s50, s3
	v_mov_b32_e32 v128, v135
	v_mov_b32_e32 v130, v136
	s_mov_b32 m0, s55
	s_nop 0
	ds_read_b128 v[64:67], v140 offset:16384
	ds_read_b128 v[68:71], v140 offset:17408
	ds_read_b128 v[72:75], v140 offset:18432
	ds_read_b128 v[76:79], v140 offset:19456
	ds_read_b128 v[80:83], v140 offset:20480
	ds_read_b128 v[84:87], v140 offset:21504
	ds_read_b128 v[88:91], v140 offset:22528
	ds_read_b128 v[92:95], v140 offset:23552
	v_mov_b32_e32 v131, v129
	global_load_lds_dwordx4 v128, s[36:37]
	s_add_i32 m0, s55, 0x2000
	v_mov_b32_e32 v128, v135
	global_load_lds_dwordx4 v130, s[36:37]
	v_mov_b32_e32 v130, v136
	s_add_i32 s55, s51, s3
	v_lshl_add_u64 v[190:191], s[36:37], 0, v[128:129]
	v_lshl_add_u64 v[190:191], v[190:191], 0, s[8:9]
	s_mov_b32 m0, s55
	v_lshl_add_u64 v[130:131], s[36:37], 0, v[130:131]
	global_load_lds_dwordx4 v[190:191], off
	v_lshl_add_u64 v[130:131], v[130:131], 0, s[8:9]
	s_add_i32 m0, s55, 0x2000
	v_mov_b32_e32 v128, v133
	global_load_lds_dwordx4 v[130:131], off
	v_mov_b32_e32 v130, v134
	s_mov_b32 m0, s41
	s_nop 0
	global_load_lds_dwordx4 v128, s[34:35]
	s_mov_b32 m0, s42
	s_nop 0
	global_load_lds_dwordx4 v130, s[34:35]
	s_and_b64 vcc, exec, s[14:15]
	s_cbranch_vccnz .Lmy_lw_6
	s_waitcnt vmcnt(8)
.Lmy_lw_6:
	s_waitcnt lgkmcnt(0)
	s_barrier
	s_setprio 1
	s_waitcnt lgkmcnt(0)
	v_mfma_scale_f32_16x16x128_f8f6f4 v[60:63], v[142:149], v[64:71], v[60:63], v141, v141 op_sel_hi:[0,0,0]
	v_mfma_scale_f32_16x16x128_f8f6f4 v[52:55], v[150:157], v[64:71], v[52:55], v141, v141 op_sel_hi:[0,0,0]
	v_mfma_scale_f32_16x16x128_f8f6f4 v[44:47], v[142:149], v[72:79], v[44:47], v141, v141 op_sel_hi:[0,0,0]
	v_mfma_scale_f32_16x16x128_f8f6f4 v[198:201], v[150:157], v[72:79], v[36:39], v141, v141 op_sel_hi:[0,0,0]
	v_mfma_scale_f32_16x16x128_f8f6f4 v[202:205], v[142:149], v[80:87], v[28:31], v141, v141 op_sel_hi:[0,0,0]
	v_mfma_scale_f32_16x16x128_f8f6f4 v[222:225], v[150:157], v[80:87], v[20:23], v141, v141 op_sel_hi:[0,0,0]
	v_mfma_scale_f32_16x16x128_f8f6f4 v[226:229], v[142:149], v[88:95], v[12:15], v141, v141 op_sel_hi:[0,0,0]
	v_mfma_scale_f32_16x16x128_f8f6f4 v[230:233], v[150:157], v[88:95], v[4:7], v141, v141 op_sel_hi:[0,0,0]
	s_setprio 0
	s_setprio 1
	v_mfma_scale_f32_16x16x128_f8f6f4 v[56:59], v[158:165], v[64:71], v[56:59], v141, v141 op_sel_hi:[0,0,0]
	v_mfma_scale_f32_16x16x128_f8f6f4 v[48:51], v[166:173], v[64:71], v[48:51], v141, v141 op_sel_hi:[0,0,0]
	v_mfma_scale_f32_16x16x128_f8f6f4 v[40:43], v[158:165], v[72:79], v[40:43], v141, v141 op_sel_hi:[0,0,0]
	v_mfma_scale_f32_16x16x128_f8f6f4 v[234:237], v[166:173], v[72:79], v[32:35], v141, v141 op_sel_hi:[0,0,0]
	v_mfma_scale_f32_16x16x128_f8f6f4 v[238:241], v[158:165], v[80:87], v[24:27], v141, v141 op_sel_hi:[0,0,0]
	v_mfma_scale_f32_16x16x128_f8f6f4 v[242:245], v[166:173], v[80:87], v[16:19], v141, v141 op_sel_hi:[0,0,0]
	v_mfma_scale_f32_16x16x128_f8f6f4 v[246:249], v[158:165], v[88:95], v[8:11], v141, v141 op_sel_hi:[0,0,0]
	v_mfma_scale_f32_16x16x128_f8f6f4 v[250:253], v[166:173], v[88:95], v[0:3], v141, v141 op_sel_hi:[0,0,0]
	s_setprio 0
	s_waitcnt vmcnt(8)
	s_barrier
	s_add_i32 s55, 0, 0x18000
	s_nop 2
	v_add_u32_e32 v8, s55, v137
	s_add_i32 s63, 0, 0x1c000
	ds_read_b128 v[0:3], v8
	ds_read_b128 v[4:7], v8 offset:1024
	ds_read_b128 v[142:145], v8 offset:2048
	ds_read_b128 v[146:149], v8 offset:3072
	v_add_u32_e32 v8, s63, v137
	ds_read_b128 v[150:153], v8
	ds_read_b128 v[154:157], v8 offset:1024
	ds_read_b128 v[158:161], v8 offset:2048
	ds_read_b128 v[162:165], v8 offset:3072
	s_add_u32 s64, s34, 0x40000
	v_mov_b32_e32 v64, v133
	v_mov_b32_e32 v65, v134
	s_addc_u32 s65, s35, 0
	s_mov_b32 m0, s43
	ds_read_b128 v[8:11], v140 offset:32768
	ds_read_b128 v[12:15], v140 offset:33792
	ds_read_b128 v[16:19], v140 offset:34816
	ds_read_b128 v[20:23], v140 offset:35840
	ds_read_b128 v[24:27], v140 offset:36864
	ds_read_b128 v[28:31], v140 offset:37888
	ds_read_b128 v[32:35], v140 offset:38912
	ds_read_b128 v[36:39], v140 offset:39936
	s_nop 0
	global_load_lds_dwordx4 v64, s[64:65]
	s_mov_b32 m0, s44
	s_nop 0
	global_load_lds_dwordx4 v65, s[64:65]
	s_and_b64 vcc, exec, s[14:15]
	s_cbranch_vccnz .Lmy_lw_7
	s_waitcnt vmcnt(8)
.Lmy_lw_7:
	s_waitcnt lgkmcnt(0)
	s_barrier
	s_setprio 1
	s_waitcnt lgkmcnt(0)
	v_mfma_scale_f32_16x16x128_f8f6f4 v[124:127], v[0:7], v[8:15], v[124:127], v141, v141 op_sel_hi:[0,0,0]
	v_mfma_scale_f32_16x16x128_f8f6f4 v[116:119], v[142:149], v[8:15], v[116:119], v141, v141 op_sel_hi:[0,0,0]
	v_mfma_scale_f32_16x16x128_f8f6f4 v[108:111], v[0:7], v[16:23], v[108:111], v141, v141 op_sel_hi:[0,0,0]
	v_mfma_scale_f32_16x16x128_f8f6f4 v[100:103], v[142:149], v[16:23], v[100:103], v141, v141 op_sel_hi:[0,0,0]
	v_mfma_scale_f32_16x16x128_f8f6f4 v[92:95], v[0:7], v[24:31], v[206:209], v141, v141 op_sel_hi:[0,0,0]
	v_mfma_scale_f32_16x16x128_f8f6f4 v[84:87], v[142:149], v[24:31], v[210:213], v141, v141 op_sel_hi:[0,0,0]
	v_mfma_scale_f32_16x16x128_f8f6f4 v[76:79], v[0:7], v[32:39], v[214:217], v141, v141 op_sel_hi:[0,0,0]
	v_mfma_scale_f32_16x16x128_f8f6f4 v[68:71], v[142:149], v[32:39], v[218:221], v141, v141 op_sel_hi:[0,0,0]
	s_setprio 0
	s_setprio 1
	v_mfma_scale_f32_16x16x128_f8f6f4 v[120:123], v[150:157], v[8:15], v[120:123], v141, v141 op_sel_hi:[0,0,0]
	v_mfma_scale_f32_16x16x128_f8f6f4 v[112:115], v[158:165], v[8:15], v[112:115], v141, v141 op_sel_hi:[0,0,0]
	v_mfma_scale_f32_16x16x128_f8f6f4 v[104:107], v[150:157], v[16:23], v[104:107], v141, v141 op_sel_hi:[0,0,0]
	v_mfma_scale_f32_16x16x128_f8f6f4 v[96:99], v[158:165], v[16:23], v[96:99], v141, v141 op_sel_hi:[0,0,0]
	v_mfma_scale_f32_16x16x128_f8f6f4 v[88:91], v[150:157], v[24:31], v[174:177], v141, v141 op_sel_hi:[0,0,0]
	v_mfma_scale_f32_16x16x128_f8f6f4 v[80:83], v[158:165], v[24:31], v[178:181], v141, v141 op_sel_hi:[0,0,0]
	v_mfma_scale_f32_16x16x128_f8f6f4 v[72:75], v[150:157], v[32:39], v[182:185], v141, v141 op_sel_hi:[0,0,0]
	v_mfma_scale_f32_16x16x128_f8f6f4 v[64:67], v[158:165], v[32:39], v[186:189], v141, v141 op_sel_hi:[0,0,0]
	s_setprio 0
	s_waitcnt vmcnt(8)
	s_barrier
	s_add_u32 s64, s36, 0x80000
	s_addc_u32 s65, s37, 0
	s_add_i32 s55, s55, s3
	v_mov_b32_e32 v8, v135
	v_mov_b32_e32 v9, v136
	s_mov_b32 m0, s55
	ds_read_b128 v[166:169], v140 offset:49152
	ds_read_b128 v[170:173], v140 offset:50176
	ds_read_b128 v[174:177], v140 offset:51200
	ds_read_b128 v[178:181], v140 offset:52224
	ds_read_b128 v[182:185], v140 offset:53248
	ds_read_b128 v[186:189], v140 offset:54272
	ds_read_b128 v[190:193], v140 offset:55296
	ds_read_b128 v[194:197], v140 offset:56320
	v_mov_b32_e32 v128, v133
	global_load_lds_dwordx4 v8, s[64:65]
	s_add_i32 m0, s55, 0x2000
	s_add_u32 s36, s36, 0x80800
	global_load_lds_dwordx4 v9, s[64:65]
	v_mov_b32_e32 v8, v135
	v_mov_b32_e32 v9, v136
	s_addc_u32 s37, s37, 0
	s_add_i32 s55, s63, s3
	s_mov_b32 m0, s55
	s_nop 0
	global_load_lds_dwordx4 v8, s[36:37]
	s_add_i32 m0, s55, 0x2000
	v_mov_b32_e32 v8, v134
	global_load_lds_dwordx4 v9, s[36:37]
	v_mov_b32_e32 v9, v129
	v_lshl_add_u64 v[10:11], s[34:35], 0, v[128:129]
	v_lshl_add_u64 v[10:11], v[10:11], 0, s[12:13]
	s_mov_b32 m0, s47
	v_lshl_add_u64 v[8:9], s[34:35], 0, v[8:9]
	global_load_lds_dwordx4 v[10:11], off
	v_lshl_add_u64 v[8:9], v[8:9], 0, s[12:13]
	s_mov_b32 m0, s48
	s_nop 0
	global_load_lds_dwordx4 v[8:9], off
	s_and_b64 vcc, exec, s[14:15]
	s_cbranch_vccnz .Lmy_lw_8
	s_waitcnt vmcnt(8)
.Lmy_lw_8:
	s_waitcnt lgkmcnt(0)
	s_barrier
	s_setprio 1
	s_waitcnt lgkmcnt(0)
	v_mfma_scale_f32_16x16x128_f8f6f4 v[60:63], v[0:7], v[166:173], v[60:63], v141, v141 op_sel_hi:[0,0,0]
	v_mfma_scale_f32_16x16x128_f8f6f4 v[52:55], v[142:149], v[166:173], v[52:55], v141, v141 op_sel_hi:[0,0,0]
	v_mfma_scale_f32_16x16x128_f8f6f4 v[44:47], v[0:7], v[174:181], v[44:47], v141, v141 op_sel_hi:[0,0,0]
	v_mfma_scale_f32_16x16x128_f8f6f4 v[36:39], v[142:149], v[174:181], v[198:201], v141, v141 op_sel_hi:[0,0,0]
	v_mfma_scale_f32_16x16x128_f8f6f4 v[28:31], v[0:7], v[182:189], v[202:205], v141, v141 op_sel_hi:[0,0,0]
	v_mfma_scale_f32_16x16x128_f8f6f4 v[20:23], v[142:149], v[182:189], v[222:225], v141, v141 op_sel_hi:[0,0,0]
	v_mfma_scale_f32_16x16x128_f8f6f4 v[12:15], v[0:7], v[190:197], v[226:229], v141, v141 op_sel_hi:[0,0,0]
	v_mfma_scale_f32_16x16x128_f8f6f4 v[4:7], v[142:149], v[190:197], v[230:233], v141, v141 op_sel_hi:[0,0,0]
	s_setprio 0
	s_setprio 1
	v_mfma_scale_f32_16x16x128_f8f6f4 v[56:59], v[150:157], v[166:173], v[56:59], v141, v141 op_sel_hi:[0,0,0]
	v_mfma_scale_f32_16x16x128_f8f6f4 v[48:51], v[158:165], v[166:173], v[48:51], v141, v141 op_sel_hi:[0,0,0]
	v_mfma_scale_f32_16x16x128_f8f6f4 v[40:43], v[150:157], v[174:181], v[40:43], v141, v141 op_sel_hi:[0,0,0]
	v_mfma_scale_f32_16x16x128_f8f6f4 v[32:35], v[158:165], v[174:181], v[234:237], v141, v141 op_sel_hi:[0,0,0]
	v_mfma_scale_f32_16x16x128_f8f6f4 v[24:27], v[150:157], v[182:189], v[238:241], v141, v141 op_sel_hi:[0,0,0]
	v_mfma_scale_f32_16x16x128_f8f6f4 v[16:19], v[158:165], v[182:189], v[242:245], v141, v141 op_sel_hi:[0,0,0]
	v_mfma_scale_f32_16x16x128_f8f6f4 v[8:11], v[150:157], v[190:197], v[246:249], v141, v141 op_sel_hi:[0,0,0]
	v_mfma_scale_f32_16x16x128_f8f6f4 v[0:3], v[158:165], v[190:197], v[250:253], v141, v141 op_sel_hi:[0,0,0]
	s_setprio 0
	s_waitcnt vmcnt(8)
	s_barrier
	s_add_i32 s54, s54, 2
	s_add_u32 s21, s21, 0x100000
	s_addc_u32 s53, s53, 0
	s_add_u32 s30, s30, 0x100
	s_addc_u32 s31, s31, 0
	s_cmp_gt_u32 s54, 13
	s_cbranch_scc0 .LBB0_2893
	s_and_b64 vcc, exec, s[14:15]
	s_cbranch_vccz .LBB0_2896
	s_barrier
